# speedup vs baseline: 1.0856x; 1.0044x over previous
.LBB0_229:
	v_add_u32_e32 v0, v14, v152
	v_exp_f32_e32 v80, v80
	v_exp_f32_e32 v81, v81
	v_exp_f32_e32 v82, v82
	v_exp_f32_e32 v83, v83
	v_exp_f32_e32 v84, v84
	v_exp_f32_e32 v85, v85
	v_exp_f32_e32 v86, v86
	v_exp_f32_e32 v87, v87
	v_add_f32_e32 v188, v80, v82
	v_add_f32_e32 v189, v81, v83
	v_cvt_pk_bf16_f32 v80, v80, v81
	v_cvt_pk_bf16_f32 v81, v82, v83
	v_cvt_pk_bf16_f32 v82, v84, v85
	v_cvt_pk_bf16_f32 v83, v86, v87
	v_add_f32_e32 v188, v188, v84
	v_add_f32_e32 v189, v189, v85
	v_add_f32_e32 v188, v188, v86
	v_add_f32_e32 v189, v189, v87
	s_waitcnt lgkmcnt(4)
	v_mfma_f32_32x32x16_bf16 v[64:79], v[176:179], v[80:83], v[64:79]
	v_exp_f32_e32 v88, v88
	v_exp_f32_e32 v89, v89
	v_exp_f32_e32 v90, v90
	v_mfma_f32_32x32x16_bf16 v[48:63], v[180:183], v[80:83], v[48:63]
	v_exp_f32_e32 v91, v91
	v_exp_f32_e32 v92, v92
	v_exp_f32_e32 v93, v93
	v_mfma_f32_32x32x16_bf16 v[32:47], v[184:187], v[80:83], v[32:47]
	v_exp_f32_e32 v94, v94
	v_exp_f32_e32 v95, v95
	v_add_f32_e32 v188, v188, v88
	v_add_f32_e32 v189, v189, v89
	v_add_f32_e32 v188, v188, v90
	v_add_f32_e32 v189, v189, v91
	v_mfma_f32_32x32x16_bf16 v[16:31], v[196:199], v[80:83], v[16:31]
	v_cvt_pk_bf16_f32 v88, v88, v89
	v_cvt_pk_bf16_f32 v89, v90, v91
	v_cvt_pk_bf16_f32 v90, v92, v93
	v_cvt_pk_bf16_f32 v91, v94, v95
	v_add_f32_e32 v188, v188, v92
	v_add_f32_e32 v189, v189, v93
	v_add_f32_e32 v188, v188, v94
	v_add_f32_e32 v189, v189, v95
	ds_read_b128 v[176:179], v0 offset:64
	ds_read_b128 v[180:183], v0 offset:8768
	ds_read_b128 v[184:187], v0 offset:17472
	ds_read_b128 v[196:199], v0 offset:26176
	s_waitcnt lgkmcnt(4)
	v_mfma_f32_32x32x16_bf16 v[64:79], v[200:203], v[88:91], v[64:79]
	v_exp_f32_e32 v96, v96
	v_exp_f32_e32 v97, v97
	v_exp_f32_e32 v98, v98
	v_mfma_f32_32x32x16_bf16 v[48:63], v[204:207], v[88:91], v[48:63]
	v_exp_f32_e32 v99, v99
	v_exp_f32_e32 v100, v100
	v_exp_f32_e32 v101, v101
	v_mfma_f32_32x32x16_bf16 v[32:47], v[244:247], v[88:91], v[32:47]
	v_exp_f32_e32 v102, v102
	v_exp_f32_e32 v103, v103
	v_add_f32_e32 v188, v188, v96
	v_add_f32_e32 v189, v189, v97
	v_add_f32_e32 v188, v188, v98
	v_add_f32_e32 v189, v189, v99
	v_mfma_f32_32x32x16_bf16 v[16:31], v[248:251], v[88:91], v[16:31]
	v_add_f32_e32 v188, v188, v100
	v_add_f32_e32 v189, v189, v101
	v_add_f32_e32 v188, v188, v102
	v_add_f32_e32 v189, v189, v103
	v_cvt_pk_bf16_f32 v84, v96, v97
	v_cvt_pk_bf16_f32 v85, v98, v99
	v_cvt_pk_bf16_f32 v86, v100, v101
	v_cvt_pk_bf16_f32 v87, v102, v103
	ds_read_b128 v[200:203], v0 offset:96
	ds_read_b128 v[204:207], v0 offset:8800
	ds_read_b128 v[244:247], v0 offset:17504
	ds_read_b128 v[248:251], v0 offset:26208
	s_waitcnt lgkmcnt(4)
	v_mfma_f32_32x32x16_bf16 v[64:79], v[176:179], v[84:87], v[64:79]
	v_exp_f32_e32 v104, v104
	v_exp_f32_e32 v105, v105
	v_exp_f32_e32 v106, v106
	v_mfma_f32_32x32x16_bf16 v[48:63], v[180:183], v[84:87], v[48:63]
	v_exp_f32_e32 v107, v107
	v_exp_f32_e32 v108, v108
	v_exp_f32_e32 v109, v109
	v_mfma_f32_32x32x16_bf16 v[32:47], v[184:187], v[84:87], v[32:47]
	v_exp_f32_e32 v110, v110
	v_exp_f32_e32 v111, v111
	v_add_f32_e32 v188, v188, v104
	v_add_f32_e32 v189, v189, v105
	v_add_f32_e32 v188, v188, v106
	v_add_f32_e32 v189, v189, v107
	v_mfma_f32_32x32x16_bf16 v[16:31], v[196:199], v[84:87], v[16:31]
	v_cvt_pk_bf16_f32 v92, v104, v105
	v_cvt_pk_bf16_f32 v93, v106, v107
	v_cvt_pk_bf16_f32 v94, v108, v109
	v_cvt_pk_bf16_f32 v95, v110, v111
	v_add_f32_e32 v188, v188, v108
	v_add_f32_e32 v189, v189, v109
	v_add_f32_e32 v188, v188, v110
	v_add_f32_e32 v189, v189, v111
	s_waitcnt lgkmcnt(0)
	v_mfma_f32_32x32x16_bf16 v[64:79], v[200:203], v[92:95], v[64:79]
	v_mfma_f32_32x32x16_bf16 v[48:63], v[204:207], v[92:95], v[48:63]
	v_add_f32_e32 v0, v188, v189
	v_mfma_f32_32x32x16_bf16 v[32:47], v[244:247], v[92:95], v[32:47]
	v_add_f32_e32 v224, v224, v0
	v_mfma_f32_32x32x16_bf16 v[16:31], v[248:251], v[92:95], v[16:31]
